# attention queues LPT-like: 24 longest prompt units first, then decode,decode,prompt; 8 shortest prompts last
# baseline (speedup 1.0000x reference)
; __device__ __forceinline__ int fresh_lane() { int l; asm volatile("v_mbcnt_lo_u32_b32 %0, -1, 0\n\tv_mbcnt_hi_u32_b32 %0, -1, %0" : "=v"(l)); return l; }
; #define SEAM(k) do { if (IN(k) && IN((k) + 1)) xcd_barrier(bar, C.wave); } while (0)
; #define PH5 { phase_attention(P, C, (P.pad >> 8) & 3, P.li); }
; #define RUN(k, BODY) do { if (IN(k)) { unsigned char* ws = P.ws; LAUNDER_GPTR(ws); BODY } } while (0)
; __device__ __forceinline__ void phase_attention(const Params& P, const Ctx& C, int parts, int qset) {
;     ...
;     for (int i = 0; i < 8; ++i) { const int x = (x0 + i) & 7;
;         for (;;) {
;             __syncthreads();
;             if (C.wave == 0 && fresh_lane() == 0) *slot = __hip_atomic_fetch_add(qc + 64 * x, 1u, __ATOMIC_RELAXED, __HIP_MEMORY_SCOPE_AGENT);
;             __syncthreads();
;             const unsigned u = *slot;
;             if (u >= 128u) break;
;             const int us = __builtin_amdgcn_readfirstlane((int)u);
; __global__ void __launch_bounds__(NWAVES * 64, 2) fwd_kernel(Params P) {
;     ...
;     RUN(3, PH3); SEAM(3);
;     RUN(4, PH4);
;     RUN(5, PH5); SEAM(5);
.LBB0_1136:
	s_bitcmp1_b32 s101, 1
	s_cbranch_scc1 .Lmy_e7
	s_bitset1_b32 s101, 1
	s_cmpk_lg_i32 s68, 0x100
	s_cbranch_scc1 .Lmy_e7
	s_bitset1_b32 s101, 3
	v_readlane_b32 s99, v254, 10
	s_cmpk_lt_u32 s99, 192
	s_cbranch_scc1 .Lmy_e7
	s_and_b32 s100, s99, 31
	s_mul_i32 s100, s100, 3
	s_add_i32 s100, s100, 24
	s_bitset1_b32 s101, 0
	s_waitcnt vmcnt(0)
	s_barrier
	s_mov_b64 s[2:3], -1
	s_branch .LBB0_1192

; __device__ __forceinline__ int fresh_lane() { int l; asm volatile("v_mbcnt_lo_u32_b32 %0, -1, 0\n\tv_mbcnt_hi_u32_b32 %0, -1, %0" : "=v"(l)); return l; }
; __device__ __forceinline__ void phase_attention(const Params& P, const Ctx& C, int parts, int qset) {
;     ...
;             __syncthreads();
;             if (C.wave == 0 && fresh_lane() == 0) *slot = __hip_atomic_fetch_add(qc + 64 * x, 1u, __ATOMIC_RELAXED, __HIP_MEMORY_SCOPE_AGENT);
;             __syncthreads();
;             const unsigned u = *slot;
;             if (u >= 128u) break;
;             const int us = __builtin_amdgcn_readfirstlane((int)u);
;             int pq = -1, dq = -1;
;             if (us < 96) { const int k = us / 3, r = us - 3 * k; if (r == 0) pq = 63 - k; else dq = 2 * k + r - 1; } else pq = 127 - us;
.LBB0_1208:
	s_waitcnt lgkmcnt(0)
	s_barrier
	ds_read_b32 v0, v218
	s_movk_i32 s2, 0x7f
	s_waitcnt lgkmcnt(0)
	v_cmp_lt_u32_e32 vcc, s2, v0
	s_mov_b64 s[2:3], -1
	s_cbranch_vccnz .LBB0_1201
	v_readfirstlane_b32 s5, v0
	s_cmpk_gt_i32 s5, 119
	s_cbranch_scc1 .LBB0_1213
	s_andn2_b64 vcc, exec, s[2:3]
	s_mov_b32 s4, -1
	s_cbranch_vccz .LBB0_1214

; __device__ __forceinline__ void phase_attention(const Params& P, const Ctx& C, int parts, int qset) {
;     ...
;             const int us = __builtin_amdgcn_readfirstlane((int)u);
;             int pq = -1, dq = -1;
;             if (us < 96) { const int k = us / 3, r = us - 3 * k; if (r == 0) pq = 63 - k; else dq = 2 * k + r - 1; } else pq = 127 - us;
;             if (pq >= 0) { if (parts & 1) { if (fixed_ok) attn_prompt_unit<true>(P, C, x, pq); else attn_prompt_unit<false>(P, C, x, pq); } }
.LBB0_1214:
	s_sub_i32 s3, s5, 24
	s_mul_hi_i32 s2, s3, 0x55555556
	s_mul_i32 s4, s2, -3
	s_add_i32 s4, s4, s3
	s_lshl_b32 s64, s2, 1
	s_add_i32 s64, s64, s4
	s_sub_i32 s2, 39, s2
	s_cmp_eq_u32 s4, 2
	s_cselect_b32 s2, s2, -1
	s_cselect_b32 s4, -1, s64
	s_sub_i32 s3, 63, s5
	s_cmpk_lt_i32 s5, 24
	s_cselect_b32 s64, s3, s2
	s_cselect_b32 s4, -1, s4
	s_cmp_lt_i32 s64, 0
	s_mov_b64 s[2:3], -1
	s_cbranch_scc0 .LBB0_1212
